# P4 epilogue: X1B/PP first-half loads of row block k+1 issued one block ahead (with block k's SSQ loads) into spare VGPRs
# speedup vs baseline: 1.0351x; 1.0013x over previous
.LBB0_477:
	v_mov_b32_e32 v144, v254
	s_lshl_b32 s21, s26, 8
	v_readfirstlane_b32 s19, v144
	s_ashr_i32 s26, s19, 2
	s_andn2_b32 s26, s26, 63
	s_add_i32 s26, s26, s21
	v_and_or_b32 v142, v144, 15, s26
	v_ashrrev_i32_e32 v143, 31, v142
	v_lshlrev_b64 v[140:141], 6, v[142:143]
	v_lshl_add_u64 v[140:141], s[6:7], 0, v[140:141]
	global_load_dwordx4 v[152:155], v[140:141], off
	global_load_dwordx4 v[156:159], v[140:141], off offset:16
	global_load_dwordx4 v[160:163], v[140:141], off offset:48
	global_load_dwordx4 v[164:167], v[140:141], off offset:32
	s_lshl_b32 s21, s49, 8
	s_and_b32 s19, s19, 0xc0
	v_lshrrev_b32_e32 v144, 1, v144
	s_or_b32 s19, s19, s21
	v_and_or_b32 v140, v144, 24, s19
	v_ashrrev_i32_e32 v141, 31, v140
	v_lshlrev_b64 v[144:145], 10, v[142:143]
	v_lshl_add_u64 v[144:145], v[144:145], 0, v[140:141]
	v_lshlrev_b64 v[172:173], 1, v[144:145]
	v_mov_b32_e32 v200, v172
	v_lshl_add_u64 v[176:177], s[16:17], 0, v[172:173]
	v_lshl_add_u64 v[178:179], s[14:15], 0, v[172:173]
	global_load_dwordx4 v[168:171], v[176:177], off
	global_load_dwordx4 v[172:175], v[178:179], off
	v_add_u32_e32 v201, 0x8000, v200
	global_load_dwordx4 v[184:187], v201, s[16:17]
	global_load_dwordx4 v[188:191], v201, s[14:15]
	v_lshl_add_u64 v[144:145], v[144:145], 2, s[30:31]
	s_waitcnt vmcnt(2)
	v_mov_b32_e32 v180, v153
	v_mov_b32_e32 v181, v154
	v_mov_b32_e32 v153, v155
	v_mov_b32_e32 v154, v157
	v_mov_b32_e32 v155, v158
	v_mov_b32_e32 v157, v159
	v_pk_add_f32 v[152:153], v[180:181], v[152:153]
	v_pk_add_f32 v[154:155], v[154:155], v[156:157]
	v_pk_add_f32 v[152:153], v[152:153], v[152:153] op_sel:[0,1] op_sel_hi:[1,0]
	v_pk_add_f32 v[154:155], v[154:155], v[154:155] op_sel:[0,1] op_sel_hi:[1,0]
	v_add_f32_e32 v158, v164, v165
	v_add_f32_e32 v164, v166, v167
	v_mov_b32_e32 v159, v162
	v_mov_b32_e32 v165, v163
	v_mov_b32_e32 v153, v160
	v_mov_b32_e32 v155, v161
	v_pk_add_f32 v[156:157], v[158:159], v[164:165]
	v_pk_add_f32 v[152:153], v[152:153], v[154:155]
	v_lshlrev_b32_e32 v158, 16, v168
	v_pk_add_f32 v[152:153], v[152:153], v[156:157]
	v_and_b32_e32 v159, 0xffff0000, v168
	v_add_f32_e32 v143, v152, v153
	v_fmamk_f32 v143, v143, 0x3a800000, v150
	v_mul_f32_e32 v151, 0x4b800000, v143
	v_cmp_gt_f32_e32 vcc, s48, v143
	v_lshlrev_b32_e32 v162, 16, v172
	v_and_b32_e32 v163, 0xffff0000, v172
	v_cndmask_b32_e32 v143, v143, v151, vcc
	v_rsq_f32_e32 v143, v143
	v_lshlrev_b32_e32 v164, 16, v169
	v_and_b32_e32 v165, 0xffff0000, v169
	v_lshlrev_b32_e32 v166, 16, v173
	v_mul_f32_e32 v151, 0x45800000, v143
	v_cndmask_b32_e32 v154, v143, v151, vcc
	v_pk_mul_f32 v[126:127], v[126:127], v[154:155] op_sel_hi:[1,0]
	v_pk_mul_f32 v[124:125], v[124:125], v[154:155] op_sel_hi:[1,0]
	v_pk_mul_f32 v[122:123], v[122:123], v[154:155] op_sel_hi:[1,0]
	v_pk_mul_f32 v[120:121], v[120:121], v[154:155] op_sel_hi:[1,0]
	v_mul_f32_e32 v124, 0xbfb8aa3b, v124
	v_mul_f32_e32 v125, 0xbfb8aa3b, v125
	v_mul_f32_e32 v126, 0xbfb8aa3b, v126
	v_mul_f32_e32 v127, 0xbfb8aa3b, v127
	v_mul_f32_e32 v120, 0xbfb8aa3b, v120
	v_mul_f32_e32 v121, 0xbfb8aa3b, v121
	v_mul_f32_e32 v122, 0xbfb8aa3b, v122
	v_mul_f32_e32 v123, 0xbfb8aa3b, v123
	v_exp_f32_e32 v124, v124
	v_exp_f32_e32 v125, v125
	v_exp_f32_e32 v126, v126
	v_exp_f32_e32 v127, v127
	v_exp_f32_e32 v120, v120
	v_exp_f32_e32 v121, v121
	v_exp_f32_e32 v122, v122
	v_exp_f32_e32 v123, v123
	v_add_f32_e32 v124, 1.0, v124
	v_add_f32_e32 v125, 1.0, v125
	v_add_f32_e32 v126, 1.0, v126
	v_add_f32_e32 v127, 1.0, v127
	v_add_f32_e32 v143, 1.0, v120
	v_add_f32_e32 v151, 1.0, v121
	v_add_f32_e32 v155, 1.0, v122
	v_add_f32_e32 v156, 1.0, v123
	v_rcp_f32_e32 v120, v124
	v_rcp_f32_e32 v121, v125
	v_rcp_f32_e32 v122, v126
	v_rcp_f32_e32 v123, v127
	v_rcp_f32_e32 v124, v143
	v_rcp_f32_e32 v125, v151
	v_rcp_f32_e32 v126, v155
	v_rcp_f32_e32 v127, v156
	v_and_b32_e32 v167, 0xffff0000, v173
	v_lshlrev_b32_e32 v168, 16, v170
	v_and_b32_e32 v169, 0xffff0000, v170
	v_lshlrev_b32_e32 v172, 16, v174
	v_and_b32_e32 v173, 0xffff0000, v174
	v_lshlrev_b32_e32 v170, 16, v171
	v_and_b32_e32 v171, 0xffff0000, v171
	v_lshlrev_b32_e32 v152, 16, v175
	v_and_b32_e32 v153, 0xffff0000, v175
	v_pk_fma_f32 v[120:121], v[120:121], v[162:163], v[158:159]
	v_pk_fma_f32 v[122:123], v[122:123], v[166:167], v[164:165]
	v_pk_fma_f32 v[124:125], v[124:125], v[172:173], v[168:169]
	v_pk_fma_f32 v[126:127], v[126:127], v[152:153], v[170:171]
	global_store_dwordx4 v[144:145], v[120:123], off nt
	global_store_dwordx4 v[144:145], v[124:127], off offset:16 nt
	global_load_dwordx4 v[120:123], v[176:177], off offset:64
	s_nop 0
	global_load_dwordx4 v[124:127], v[178:179], off offset:64
	v_pk_mul_f32 v[118:119], v[118:119], v[154:155] op_sel_hi:[1,0]
	v_pk_mul_f32 v[116:117], v[116:117], v[154:155] op_sel_hi:[1,0]
	v_pk_mul_f32 v[114:115], v[114:115], v[154:155] op_sel_hi:[1,0]
	v_pk_mul_f32 v[112:113], v[112:113], v[154:155] op_sel_hi:[1,0]
	v_mul_f32_e32 v116, 0xbfb8aa3b, v116
	v_mul_f32_e32 v117, 0xbfb8aa3b, v117
	v_mul_f32_e32 v118, 0xbfb8aa3b, v118
	v_mul_f32_e32 v119, 0xbfb8aa3b, v119
	v_mul_f32_e32 v112, 0xbfb8aa3b, v112
	v_mul_f32_e32 v113, 0xbfb8aa3b, v113
	v_mul_f32_e32 v114, 0xbfb8aa3b, v114
	v_mul_f32_e32 v115, 0xbfb8aa3b, v115
	v_exp_f32_e32 v116, v116
	v_exp_f32_e32 v117, v117
	v_exp_f32_e32 v118, v118
	v_exp_f32_e32 v119, v119
	v_exp_f32_e32 v112, v112
	v_exp_f32_e32 v113, v113
	v_exp_f32_e32 v114, v114
	v_exp_f32_e32 v115, v115
	v_add_f32_e32 v116, 1.0, v116
	v_add_f32_e32 v117, 1.0, v117
	v_add_f32_e32 v118, 1.0, v118
	v_add_f32_e32 v119, 1.0, v119
	v_add_f32_e32 v143, 1.0, v112
	v_add_f32_e32 v151, 1.0, v113
	v_add_f32_e32 v154, 1.0, v114
	v_add_f32_e32 v155, 1.0, v115
	v_rcp_f32_e32 v112, v116
	v_rcp_f32_e32 v113, v117
	v_rcp_f32_e32 v114, v118
	v_rcp_f32_e32 v115, v119
	v_rcp_f32_e32 v116, v143
	v_rcp_f32_e32 v117, v151
	v_rcp_f32_e32 v118, v154
	v_rcp_f32_e32 v119, v155
	v_or_b32_e32 v152, 16, v142
	v_ashrrev_i32_e32 v153, 31, v152
	v_lshlrev_b64 v[156:157], 6, v[152:153]
	v_lshl_add_u64 v[156:157], s[6:7], 0, v[156:157]
	s_waitcnt vmcnt(1)
	v_lshlrev_b32_e32 v154, 16, v120
	v_and_b32_e32 v155, 0xffff0000, v120
	s_waitcnt vmcnt(0)
	v_lshlrev_b32_e32 v158, 16, v124
	v_and_b32_e32 v159, 0xffff0000, v124
	v_lshlrev_b32_e32 v120, 16, v121
	v_and_b32_e32 v121, 0xffff0000, v121
	v_lshlrev_b32_e32 v124, 16, v125
	v_and_b32_e32 v125, 0xffff0000, v125
	v_lshlrev_b32_e32 v160, 16, v122
	v_and_b32_e32 v161, 0xffff0000, v122
	v_lshlrev_b32_e32 v162, 16, v126
	v_and_b32_e32 v163, 0xffff0000, v126
	v_lshlrev_b32_e32 v122, 16, v123
	v_and_b32_e32 v123, 0xffff0000, v123
	v_lshlrev_b32_e32 v126, 16, v127
	v_and_b32_e32 v127, 0xffff0000, v127
	v_pk_fma_f32 v[112:113], v[112:113], v[158:159], v[154:155]
	v_pk_fma_f32 v[114:115], v[114:115], v[124:125], v[120:121]
	v_pk_fma_f32 v[116:117], v[116:117], v[162:163], v[160:161]
	v_pk_fma_f32 v[118:119], v[118:119], v[126:127], v[122:123]
	global_store_dwordx4 v[144:145], v[112:115], off offset:128 nt
	global_store_dwordx4 v[144:145], v[116:119], off offset:144 nt
	global_load_dwordx4 v[114:117], v[156:157], off
	s_nop 0
	global_load_dwordx4 v[118:121], v[156:157], off offset:16
	v_lshlrev_b64 v[112:113], 10, v[152:153]
	global_load_dwordx4 v[122:125], v[156:157], off offset:48
	global_load_dwordx4 v[152:155], v[156:157], off offset:32
	v_lshl_add_u64 v[112:113], v[112:113], 0, v[140:141]
	v_lshlrev_b64 v[126:127], 1, v[112:113]
	v_lshl_add_u64 v[144:145], s[16:17], 0, v[126:127]
	v_lshl_add_u64 v[126:127], s[14:15], 0, v[126:127]
	v_add_u32_e32 v201, 0x10000, v200
	global_load_dwordx4 v[192:195], v201, s[16:17]
	global_load_dwordx4 v[196:199], v201, s[14:15]
	v_lshl_add_u64 v[112:113], v[112:113], 2, s[30:31]
	s_waitcnt vmcnt(5)
	v_mov_b32_e32 v164, v115
	v_mov_b32_e32 v165, v116
	v_mov_b32_e32 v115, v117
	s_waitcnt vmcnt(4)
	v_mov_b32_e32 v116, v119
	v_mov_b32_e32 v117, v120
	v_mov_b32_e32 v119, v121
	v_pk_add_f32 v[114:115], v[164:165], v[114:115]
	v_pk_add_f32 v[116:117], v[116:117], v[118:119]
	v_pk_add_f32 v[114:115], v[114:115], v[114:115] op_sel:[0,1] op_sel_hi:[1,0]
	v_pk_add_f32 v[116:117], v[116:117], v[116:117] op_sel:[0,1] op_sel_hi:[1,0]
	s_waitcnt vmcnt(2)
	v_add_f32_e32 v120, v152, v153
	v_add_f32_e32 v152, v154, v155
	v_mov_b32_e32 v121, v124
	v_mov_b32_e32 v153, v125
	v_mov_b32_e32 v115, v122
	v_mov_b32_e32 v117, v123
	v_pk_add_f32 v[118:119], v[120:121], v[152:153]
	v_pk_add_f32 v[114:115], v[114:115], v[116:117]
	s_waitcnt vmcnt(2)
	v_lshlrev_b32_e32 v124, 16, v184
	v_pk_add_f32 v[114:115], v[114:115], v[118:119]
	v_and_b32_e32 v125, 0xffff0000, v184
	v_add_f32_e32 v114, v114, v115
	v_fmamk_f32 v114, v114, 0x3a800000, v150
	v_mul_f32_e32 v115, 0x4b800000, v114
	v_cmp_gt_f32_e32 vcc, s48, v114
	s_waitcnt vmcnt(2)
	v_lshlrev_b32_e32 v154, 16, v188
	v_and_b32_e32 v155, 0xffff0000, v188
	v_cndmask_b32_e32 v114, v114, v115, vcc
	v_rsq_f32_e32 v116, v114
	v_lshlrev_b32_e32 v156, 16, v185
	v_and_b32_e32 v157, 0xffff0000, v185
	v_lshlrev_b32_e32 v160, 16, v189
	v_mul_f32_e32 v117, 0x45800000, v116
	v_cndmask_b32_e32 v116, v116, v117, vcc
	v_pk_mul_f32 v[110:111], v[110:111], v[116:117] op_sel_hi:[1,0]
	v_pk_mul_f32 v[108:109], v[108:109], v[116:117] op_sel_hi:[1,0]
	v_pk_mul_f32 v[106:107], v[106:107], v[116:117] op_sel_hi:[1,0]
	v_pk_mul_f32 v[104:105], v[104:105], v[116:117] op_sel_hi:[1,0]
	v_mul_f32_e32 v108, 0xbfb8aa3b, v108
	v_mul_f32_e32 v109, 0xbfb8aa3b, v109
	v_mul_f32_e32 v110, 0xbfb8aa3b, v110
	v_mul_f32_e32 v111, 0xbfb8aa3b, v111
	v_mul_f32_e32 v104, 0xbfb8aa3b, v104
	v_mul_f32_e32 v105, 0xbfb8aa3b, v105
	v_mul_f32_e32 v106, 0xbfb8aa3b, v106
	v_mul_f32_e32 v107, 0xbfb8aa3b, v107
	v_exp_f32_e32 v108, v108
	v_exp_f32_e32 v109, v109
	v_exp_f32_e32 v110, v110
	v_exp_f32_e32 v111, v111
	v_exp_f32_e32 v104, v104
	v_exp_f32_e32 v105, v105
	v_exp_f32_e32 v106, v106
	v_exp_f32_e32 v107, v107
	v_add_f32_e32 v108, 1.0, v108
	v_add_f32_e32 v109, 1.0, v109
	v_add_f32_e32 v110, 1.0, v110
	v_add_f32_e32 v111, 1.0, v111
	v_add_f32_e32 v117, 1.0, v104
	v_add_f32_e32 v118, 1.0, v105
	v_add_f32_e32 v119, 1.0, v106
	v_add_f32_e32 v120, 1.0, v107
	v_rcp_f32_e32 v104, v108
	v_rcp_f32_e32 v105, v109
	v_rcp_f32_e32 v106, v110
	v_rcp_f32_e32 v107, v111
	v_rcp_f32_e32 v108, v117
	v_rcp_f32_e32 v109, v118
	v_rcp_f32_e32 v110, v119
	v_rcp_f32_e32 v111, v120
	v_and_b32_e32 v161, 0xffff0000, v189
	v_lshlrev_b32_e32 v166, 16, v186
	v_and_b32_e32 v167, 0xffff0000, v186
	v_lshlrev_b32_e32 v168, 16, v190
	v_and_b32_e32 v169, 0xffff0000, v190
	v_lshlrev_b32_e32 v158, 16, v187
	v_and_b32_e32 v159, 0xffff0000, v187
	v_lshlrev_b32_e32 v114, 16, v191
	v_and_b32_e32 v115, 0xffff0000, v191
	v_pk_fma_f32 v[104:105], v[104:105], v[154:155], v[124:125]
	v_pk_fma_f32 v[106:107], v[106:107], v[160:161], v[156:157]
	v_pk_fma_f32 v[108:109], v[108:109], v[168:169], v[166:167]
	v_pk_fma_f32 v[110:111], v[110:111], v[114:115], v[158:159]
	global_store_dwordx4 v[112:113], v[104:107], off nt
	global_store_dwordx4 v[112:113], v[108:111], off offset:16 nt
	global_load_dwordx4 v[104:107], v[144:145], off offset:64
	s_nop 0
	global_load_dwordx4 v[108:111], v[126:127], off offset:64
	v_pk_mul_f32 v[102:103], v[102:103], v[116:117] op_sel_hi:[1,0]
	v_pk_mul_f32 v[100:101], v[100:101], v[116:117] op_sel_hi:[1,0]
	v_pk_mul_f32 v[98:99], v[98:99], v[116:117] op_sel_hi:[1,0]
	v_pk_mul_f32 v[96:97], v[96:97], v[116:117] op_sel_hi:[1,0]
	v_mul_f32_e32 v100, 0xbfb8aa3b, v100
	v_mul_f32_e32 v101, 0xbfb8aa3b, v101
	v_mul_f32_e32 v102, 0xbfb8aa3b, v102
	v_mul_f32_e32 v103, 0xbfb8aa3b, v103
	v_mul_f32_e32 v96, 0xbfb8aa3b, v96
	v_mul_f32_e32 v97, 0xbfb8aa3b, v97
	v_mul_f32_e32 v98, 0xbfb8aa3b, v98
	v_mul_f32_e32 v99, 0xbfb8aa3b, v99
	v_exp_f32_e32 v100, v100
	v_exp_f32_e32 v101, v101
	v_exp_f32_e32 v102, v102
	v_exp_f32_e32 v103, v103
	v_exp_f32_e32 v96, v96
	v_exp_f32_e32 v97, v97
	v_exp_f32_e32 v98, v98
	v_exp_f32_e32 v99, v99
	v_add_f32_e32 v100, 1.0, v100
	v_add_f32_e32 v101, 1.0, v101
	v_add_f32_e32 v102, 1.0, v102
	v_add_f32_e32 v103, 1.0, v103
	v_add_f32_e32 v116, 1.0, v96
	v_add_f32_e32 v117, 1.0, v97
	v_add_f32_e32 v120, 1.0, v98
	v_add_f32_e32 v121, 1.0, v99
	v_rcp_f32_e32 v96, v100
	v_rcp_f32_e32 v97, v101
	v_rcp_f32_e32 v98, v102
	v_rcp_f32_e32 v99, v103
	v_rcp_f32_e32 v100, v116
	v_rcp_f32_e32 v101, v117
	v_rcp_f32_e32 v102, v120
	v_rcp_f32_e32 v103, v121
	v_or_b32_e32 v114, 32, v142
	v_ashrrev_i32_e32 v115, 31, v114
	v_lshlrev_b64 v[118:119], 6, v[114:115]
	v_lshl_add_u64 v[118:119], s[6:7], 0, v[118:119]
	s_waitcnt vmcnt(1)
	v_lshlrev_b32_e32 v116, 16, v104
	v_and_b32_e32 v117, 0xffff0000, v104
	s_waitcnt vmcnt(0)
	v_lshlrev_b32_e32 v120, 16, v108
	v_and_b32_e32 v121, 0xffff0000, v108
	v_lshlrev_b32_e32 v104, 16, v105
	v_and_b32_e32 v105, 0xffff0000, v105
	v_lshlrev_b32_e32 v108, 16, v109
	v_and_b32_e32 v109, 0xffff0000, v109
	v_lshlrev_b32_e32 v122, 16, v106
	v_and_b32_e32 v123, 0xffff0000, v106
	v_lshlrev_b32_e32 v124, 16, v110
	v_and_b32_e32 v125, 0xffff0000, v110
	v_lshlrev_b32_e32 v106, 16, v107
	v_and_b32_e32 v107, 0xffff0000, v107
	v_lshlrev_b32_e32 v110, 16, v111
	v_and_b32_e32 v111, 0xffff0000, v111
	v_pk_fma_f32 v[96:97], v[96:97], v[120:121], v[116:117]
	v_pk_fma_f32 v[98:99], v[98:99], v[108:109], v[104:105]
	v_pk_fma_f32 v[100:101], v[100:101], v[124:125], v[122:123]
	v_pk_fma_f32 v[102:103], v[102:103], v[110:111], v[106:107]
	global_store_dwordx4 v[112:113], v[96:99], off offset:128 nt
	global_store_dwordx4 v[112:113], v[100:103], off offset:144 nt
	global_load_dwordx4 v[98:101], v[118:119], off
	s_nop 0
	global_load_dwordx4 v[102:105], v[118:119], off offset:16
	global_load_dwordx4 v[106:109], v[118:119], off offset:48
	global_load_dwordx4 v[110:113], v[118:119], off offset:32
	v_lshlrev_b64 v[96:97], 10, v[114:115]
	v_lshl_add_u64 v[96:97], v[96:97], 0, v[140:141]
	v_lshlrev_b64 v[118:119], 1, v[96:97]
	v_lshl_add_u64 v[122:123], s[16:17], 0, v[118:119]
	v_lshl_add_u64 v[124:125], s[14:15], 0, v[118:119]
	v_add_u32_e32 v201, 0x18000, v200
	global_load_dwordx4 v[184:187], v201, s[16:17]
	global_load_dwordx4 v[188:191], v201, s[14:15]
	v_lshl_add_u64 v[96:97], v[96:97], 2, s[30:31]
	s_waitcnt vmcnt(5)
	v_mov_b32_e32 v126, v99
	v_mov_b32_e32 v127, v100
	v_mov_b32_e32 v99, v101
	s_waitcnt vmcnt(4)
	v_mov_b32_e32 v100, v103
	v_mov_b32_e32 v101, v104
	v_mov_b32_e32 v103, v105
	v_pk_add_f32 v[98:99], v[126:127], v[98:99]
	v_pk_add_f32 v[100:101], v[100:101], v[102:103]
	v_pk_add_f32 v[98:99], v[98:99], v[98:99] op_sel:[0,1] op_sel_hi:[1,0]
	v_pk_add_f32 v[100:101], v[100:101], v[100:101] op_sel:[0,1] op_sel_hi:[1,0]
	s_waitcnt vmcnt(2)
	v_add_f32_e32 v104, v110, v111
	v_add_f32_e32 v110, v112, v113
	v_mov_b32_e32 v105, v108
	v_mov_b32_e32 v111, v109
	v_mov_b32_e32 v99, v106
	v_mov_b32_e32 v101, v107
	v_pk_add_f32 v[102:103], v[104:105], v[110:111]
	v_pk_add_f32 v[98:99], v[98:99], v[100:101]
	s_waitcnt vmcnt(2)
	v_lshlrev_b32_e32 v108, 16, v192
	v_pk_add_f32 v[98:99], v[98:99], v[102:103]
	v_and_b32_e32 v109, 0xffff0000, v192
	v_add_f32_e32 v98, v98, v99
	v_fmamk_f32 v98, v98, 0x3a800000, v150
	v_mul_f32_e32 v99, 0x4b800000, v98
	v_cmp_gt_f32_e32 vcc, s48, v98
	s_waitcnt vmcnt(2)
	v_lshlrev_b32_e32 v112, 16, v196
	v_and_b32_e32 v113, 0xffff0000, v196
	v_cndmask_b32_e32 v98, v98, v99, vcc
	v_rsq_f32_e32 v100, v98
	v_lshlrev_b32_e32 v114, 16, v193
	v_and_b32_e32 v115, 0xffff0000, v193
	v_lshlrev_b32_e32 v118, 16, v197
	v_mul_f32_e32 v101, 0x45800000, v100
	v_cndmask_b32_e32 v100, v100, v101, vcc
	v_pk_mul_f32 v[94:95], v[94:95], v[100:101] op_sel_hi:[1,0]
	v_pk_mul_f32 v[92:93], v[92:93], v[100:101] op_sel_hi:[1,0]
	v_pk_mul_f32 v[90:91], v[90:91], v[100:101] op_sel_hi:[1,0]
	v_pk_mul_f32 v[88:89], v[88:89], v[100:101] op_sel_hi:[1,0]
	v_mul_f32_e32 v92, 0xbfb8aa3b, v92
	v_mul_f32_e32 v93, 0xbfb8aa3b, v93
	v_mul_f32_e32 v94, 0xbfb8aa3b, v94
	v_mul_f32_e32 v95, 0xbfb8aa3b, v95
	v_mul_f32_e32 v88, 0xbfb8aa3b, v88
	v_mul_f32_e32 v89, 0xbfb8aa3b, v89
	v_mul_f32_e32 v90, 0xbfb8aa3b, v90
	v_mul_f32_e32 v91, 0xbfb8aa3b, v91
	v_exp_f32_e32 v92, v92
	v_exp_f32_e32 v93, v93
	v_exp_f32_e32 v94, v94
	v_exp_f32_e32 v95, v95
	v_exp_f32_e32 v88, v88
	v_exp_f32_e32 v89, v89
	v_exp_f32_e32 v90, v90
	v_exp_f32_e32 v91, v91
	v_add_f32_e32 v92, 1.0, v92
	v_add_f32_e32 v93, 1.0, v93
	v_add_f32_e32 v94, 1.0, v94
	v_add_f32_e32 v95, 1.0, v95
	v_add_f32_e32 v101, 1.0, v88
	v_add_f32_e32 v102, 1.0, v89
	v_add_f32_e32 v103, 1.0, v90
	v_add_f32_e32 v104, 1.0, v91
	v_rcp_f32_e32 v88, v92
	v_rcp_f32_e32 v89, v93
	v_rcp_f32_e32 v90, v94
	v_rcp_f32_e32 v91, v95
	v_rcp_f32_e32 v92, v101
	v_rcp_f32_e32 v93, v102
	v_rcp_f32_e32 v94, v103
	v_rcp_f32_e32 v95, v104
	v_and_b32_e32 v119, 0xffff0000, v197
	v_lshlrev_b32_e32 v144, 16, v194
	v_and_b32_e32 v145, 0xffff0000, v194
	v_lshlrev_b32_e32 v152, 16, v198
	v_and_b32_e32 v153, 0xffff0000, v198
	v_lshlrev_b32_e32 v116, 16, v195
	v_and_b32_e32 v117, 0xffff0000, v195
	v_lshlrev_b32_e32 v98, 16, v199
	v_and_b32_e32 v99, 0xffff0000, v199
	v_pk_fma_f32 v[88:89], v[88:89], v[112:113], v[108:109]
	v_pk_fma_f32 v[90:91], v[90:91], v[118:119], v[114:115]
	v_pk_fma_f32 v[92:93], v[92:93], v[152:153], v[144:145]
	v_pk_fma_f32 v[94:95], v[94:95], v[98:99], v[116:117]
	global_store_dwordx4 v[96:97], v[88:91], off nt
	global_store_dwordx4 v[96:97], v[92:95], off offset:16 nt
	global_load_dwordx4 v[88:91], v[122:123], off offset:64
	s_nop 0
	global_load_dwordx4 v[92:95], v[124:125], off offset:64
	v_pk_mul_f32 v[86:87], v[86:87], v[100:101] op_sel_hi:[1,0]
	v_pk_mul_f32 v[84:85], v[84:85], v[100:101] op_sel_hi:[1,0]
	v_pk_mul_f32 v[82:83], v[82:83], v[100:101] op_sel_hi:[1,0]
	v_pk_mul_f32 v[80:81], v[80:81], v[100:101] op_sel_hi:[1,0]
	v_mul_f32_e32 v84, 0xbfb8aa3b, v84
	v_mul_f32_e32 v85, 0xbfb8aa3b, v85
	v_mul_f32_e32 v86, 0xbfb8aa3b, v86
	v_mul_f32_e32 v87, 0xbfb8aa3b, v87
	v_mul_f32_e32 v80, 0xbfb8aa3b, v80
	v_mul_f32_e32 v81, 0xbfb8aa3b, v81
	v_mul_f32_e32 v82, 0xbfb8aa3b, v82
	v_mul_f32_e32 v83, 0xbfb8aa3b, v83
	v_exp_f32_e32 v84, v84
	v_exp_f32_e32 v85, v85
	v_exp_f32_e32 v86, v86
	v_exp_f32_e32 v87, v87
	v_exp_f32_e32 v80, v80
	v_exp_f32_e32 v81, v81
	v_exp_f32_e32 v82, v82
	v_exp_f32_e32 v83, v83
	v_add_f32_e32 v84, 1.0, v84
	v_add_f32_e32 v85, 1.0, v85
	v_add_f32_e32 v86, 1.0, v86
	v_add_f32_e32 v87, 1.0, v87
	v_add_f32_e32 v100, 1.0, v80
	v_add_f32_e32 v101, 1.0, v81
	v_add_f32_e32 v104, 1.0, v82
	v_add_f32_e32 v105, 1.0, v83
	v_rcp_f32_e32 v80, v84
	v_rcp_f32_e32 v81, v85
	v_rcp_f32_e32 v82, v86
	v_rcp_f32_e32 v83, v87
	v_rcp_f32_e32 v84, v100
	v_rcp_f32_e32 v85, v101
	v_rcp_f32_e32 v86, v104
	v_rcp_f32_e32 v87, v105
	v_or_b32_e32 v98, 48, v142
	v_ashrrev_i32_e32 v99, 31, v98
	v_lshlrev_b64 v[102:103], 6, v[98:99]
	v_lshl_add_u64 v[102:103], s[6:7], 0, v[102:103]
	s_waitcnt vmcnt(1)
	v_lshlrev_b32_e32 v100, 16, v88
	v_and_b32_e32 v101, 0xffff0000, v88
	s_waitcnt vmcnt(0)
	v_lshlrev_b32_e32 v104, 16, v92
	v_and_b32_e32 v105, 0xffff0000, v92
	v_lshlrev_b32_e32 v88, 16, v89
	v_and_b32_e32 v89, 0xffff0000, v89
	v_lshlrev_b32_e32 v92, 16, v93
	v_and_b32_e32 v93, 0xffff0000, v93
	v_lshlrev_b32_e32 v106, 16, v90
	v_and_b32_e32 v107, 0xffff0000, v90
	v_lshlrev_b32_e32 v108, 16, v94
	v_and_b32_e32 v109, 0xffff0000, v94
	v_lshlrev_b32_e32 v90, 16, v91
	v_and_b32_e32 v91, 0xffff0000, v91
	v_lshlrev_b32_e32 v94, 16, v95
	v_and_b32_e32 v95, 0xffff0000, v95
	v_pk_fma_f32 v[80:81], v[80:81], v[104:105], v[100:101]
	v_pk_fma_f32 v[82:83], v[82:83], v[92:93], v[88:89]
	v_pk_fma_f32 v[84:85], v[84:85], v[108:109], v[106:107]
	v_pk_fma_f32 v[86:87], v[86:87], v[94:95], v[90:91]
	global_store_dwordx4 v[96:97], v[80:83], off offset:128 nt
	global_store_dwordx4 v[96:97], v[84:87], off offset:144 nt
	global_load_dwordx4 v[82:85], v[102:103], off
	s_nop 0
	global_load_dwordx4 v[86:89], v[102:103], off offset:16
	global_load_dwordx4 v[90:93], v[102:103], off offset:48
	global_load_dwordx4 v[94:97], v[102:103], off offset:32
	v_lshlrev_b64 v[80:81], 10, v[98:99]
	v_lshl_add_u64 v[80:81], v[80:81], 0, v[140:141]
	v_lshlrev_b64 v[102:103], 1, v[80:81]
	v_lshl_add_u64 v[106:107], s[16:17], 0, v[102:103]
	v_lshl_add_u64 v[108:109], s[14:15], 0, v[102:103]
	v_add_u32_e32 v201, 0x40000, v200
	global_load_dwordx4 v[192:195], v201, s[16:17]
	global_load_dwordx4 v[196:199], v201, s[14:15]
	v_lshl_add_u64 v[80:81], v[80:81], 2, s[30:31]
	s_waitcnt vmcnt(5)
	v_mov_b32_e32 v110, v83
	v_mov_b32_e32 v111, v84
	v_mov_b32_e32 v83, v85
	s_waitcnt vmcnt(4)
	v_mov_b32_e32 v84, v87
	v_mov_b32_e32 v85, v88
	v_mov_b32_e32 v87, v89
	v_pk_add_f32 v[82:83], v[110:111], v[82:83]
	v_pk_add_f32 v[84:85], v[84:85], v[86:87]
	v_pk_add_f32 v[82:83], v[82:83], v[82:83] op_sel:[0,1] op_sel_hi:[1,0]
	v_pk_add_f32 v[84:85], v[84:85], v[84:85] op_sel:[0,1] op_sel_hi:[1,0]
	s_waitcnt vmcnt(2)
	v_add_f32_e32 v88, v94, v95
	v_add_f32_e32 v94, v96, v97
	v_mov_b32_e32 v89, v92
	v_mov_b32_e32 v95, v93
	v_mov_b32_e32 v83, v90
	v_mov_b32_e32 v85, v91
	v_pk_add_f32 v[86:87], v[88:89], v[94:95]
	v_pk_add_f32 v[82:83], v[82:83], v[84:85]
	s_waitcnt vmcnt(2)
	v_lshlrev_b32_e32 v92, 16, v184
	v_pk_add_f32 v[82:83], v[82:83], v[86:87]
	v_and_b32_e32 v93, 0xffff0000, v184
	v_add_f32_e32 v82, v82, v83
	v_fmamk_f32 v82, v82, 0x3a800000, v150
	v_mul_f32_e32 v83, 0x4b800000, v82
	v_cmp_gt_f32_e32 vcc, s48, v82
	s_waitcnt vmcnt(2)
	v_lshlrev_b32_e32 v96, 16, v188
	v_and_b32_e32 v97, 0xffff0000, v188
	v_cndmask_b32_e32 v82, v82, v83, vcc
	v_rsq_f32_e32 v84, v82
	v_lshlrev_b32_e32 v98, 16, v185
	v_and_b32_e32 v99, 0xffff0000, v185
	v_lshlrev_b32_e32 v102, 16, v189
	v_mul_f32_e32 v85, 0x45800000, v84
	v_cndmask_b32_e32 v84, v84, v85, vcc
	v_pk_mul_f32 v[78:79], v[78:79], v[84:85] op_sel_hi:[1,0]
	v_pk_mul_f32 v[76:77], v[76:77], v[84:85] op_sel_hi:[1,0]
	v_pk_mul_f32 v[74:75], v[74:75], v[84:85] op_sel_hi:[1,0]
	v_pk_mul_f32 v[72:73], v[72:73], v[84:85] op_sel_hi:[1,0]
	v_mul_f32_e32 v76, 0xbfb8aa3b, v76
	v_mul_f32_e32 v77, 0xbfb8aa3b, v77
	v_mul_f32_e32 v78, 0xbfb8aa3b, v78
	v_mul_f32_e32 v79, 0xbfb8aa3b, v79
	v_mul_f32_e32 v72, 0xbfb8aa3b, v72
	v_mul_f32_e32 v73, 0xbfb8aa3b, v73
	v_mul_f32_e32 v74, 0xbfb8aa3b, v74
	v_mul_f32_e32 v75, 0xbfb8aa3b, v75
	v_exp_f32_e32 v76, v76
	v_exp_f32_e32 v77, v77
	v_exp_f32_e32 v78, v78
	v_exp_f32_e32 v79, v79
	v_exp_f32_e32 v72, v72
	v_exp_f32_e32 v73, v73
	v_exp_f32_e32 v74, v74
	v_exp_f32_e32 v75, v75
	v_add_f32_e32 v76, 1.0, v76
	v_add_f32_e32 v77, 1.0, v77
	v_add_f32_e32 v78, 1.0, v78
	v_add_f32_e32 v79, 1.0, v79
	v_add_f32_e32 v85, 1.0, v72
	v_add_f32_e32 v86, 1.0, v73
	v_add_f32_e32 v87, 1.0, v74
	v_add_f32_e32 v88, 1.0, v75
	v_rcp_f32_e32 v72, v76
	v_rcp_f32_e32 v73, v77
	v_rcp_f32_e32 v74, v78
	v_rcp_f32_e32 v75, v79
	v_rcp_f32_e32 v76, v85
	v_rcp_f32_e32 v77, v86
	v_rcp_f32_e32 v78, v87
	v_rcp_f32_e32 v79, v88
	v_and_b32_e32 v103, 0xffff0000, v189
	v_lshlrev_b32_e32 v112, 16, v186
	v_and_b32_e32 v113, 0xffff0000, v186
	v_lshlrev_b32_e32 v114, 16, v190
	v_and_b32_e32 v115, 0xffff0000, v190
	v_lshlrev_b32_e32 v100, 16, v187
	v_and_b32_e32 v101, 0xffff0000, v187
	v_lshlrev_b32_e32 v82, 16, v191
	v_and_b32_e32 v83, 0xffff0000, v191
	v_pk_fma_f32 v[72:73], v[72:73], v[96:97], v[92:93]
	v_pk_fma_f32 v[74:75], v[74:75], v[102:103], v[98:99]
	v_pk_fma_f32 v[76:77], v[76:77], v[114:115], v[112:113]
	v_pk_fma_f32 v[78:79], v[78:79], v[82:83], v[100:101]
	global_store_dwordx4 v[80:81], v[72:75], off nt
	global_store_dwordx4 v[80:81], v[76:79], off offset:16 nt
	global_load_dwordx4 v[72:75], v[106:107], off offset:64
	s_nop 0
	global_load_dwordx4 v[76:79], v[108:109], off offset:64
	v_pk_mul_f32 v[70:71], v[70:71], v[84:85] op_sel_hi:[1,0]
	v_pk_mul_f32 v[68:69], v[68:69], v[84:85] op_sel_hi:[1,0]
	v_pk_mul_f32 v[66:67], v[66:67], v[84:85] op_sel_hi:[1,0]
	v_pk_mul_f32 v[64:65], v[64:65], v[84:85] op_sel_hi:[1,0]
	v_mul_f32_e32 v68, 0xbfb8aa3b, v68
	v_mul_f32_e32 v69, 0xbfb8aa3b, v69
	v_mul_f32_e32 v70, 0xbfb8aa3b, v70
	v_mul_f32_e32 v71, 0xbfb8aa3b, v71
	v_mul_f32_e32 v64, 0xbfb8aa3b, v64
	v_mul_f32_e32 v65, 0xbfb8aa3b, v65
	v_mul_f32_e32 v66, 0xbfb8aa3b, v66
	v_mul_f32_e32 v67, 0xbfb8aa3b, v67
	v_exp_f32_e32 v68, v68
	v_exp_f32_e32 v69, v69
	v_exp_f32_e32 v70, v70
	v_exp_f32_e32 v71, v71
	v_exp_f32_e32 v64, v64
	v_exp_f32_e32 v65, v65
	v_exp_f32_e32 v66, v66
	v_exp_f32_e32 v67, v67
	v_add_f32_e32 v68, 1.0, v68
	v_add_f32_e32 v69, 1.0, v69
	v_add_f32_e32 v70, 1.0, v70
	v_add_f32_e32 v71, 1.0, v71
	v_add_f32_e32 v84, 1.0, v64
	v_add_f32_e32 v85, 1.0, v65
	v_add_f32_e32 v88, 1.0, v66
	v_add_f32_e32 v89, 1.0, v67
	v_rcp_f32_e32 v64, v68
	v_rcp_f32_e32 v65, v69
	v_rcp_f32_e32 v66, v70
	v_rcp_f32_e32 v67, v71
	v_rcp_f32_e32 v68, v84
	v_rcp_f32_e32 v69, v85
	v_rcp_f32_e32 v70, v88
	v_rcp_f32_e32 v71, v89
	v_add_u32_e32 v82, 0x80, v142
	v_ashrrev_i32_e32 v83, 31, v82
	v_lshlrev_b64 v[86:87], 6, v[82:83]
	v_lshl_add_u64 v[86:87], s[6:7], 0, v[86:87]
	s_waitcnt vmcnt(1)
	v_lshlrev_b32_e32 v84, 16, v72
	v_and_b32_e32 v85, 0xffff0000, v72
	s_waitcnt vmcnt(0)
	v_lshlrev_b32_e32 v88, 16, v76
	v_and_b32_e32 v89, 0xffff0000, v76
	v_lshlrev_b32_e32 v72, 16, v73
	v_and_b32_e32 v73, 0xffff0000, v73
	v_lshlrev_b32_e32 v76, 16, v77
	v_and_b32_e32 v77, 0xffff0000, v77
	v_lshlrev_b32_e32 v90, 16, v74
	v_and_b32_e32 v91, 0xffff0000, v74
	v_lshlrev_b32_e32 v92, 16, v78
	v_and_b32_e32 v93, 0xffff0000, v78
	v_lshlrev_b32_e32 v74, 16, v75
	v_and_b32_e32 v75, 0xffff0000, v75
	v_lshlrev_b32_e32 v78, 16, v79
	v_and_b32_e32 v79, 0xffff0000, v79
	v_pk_fma_f32 v[64:65], v[64:65], v[88:89], v[84:85]
	v_pk_fma_f32 v[66:67], v[66:67], v[76:77], v[72:73]
	v_pk_fma_f32 v[68:69], v[68:69], v[92:93], v[90:91]
	v_pk_fma_f32 v[70:71], v[70:71], v[78:79], v[74:75]
	global_store_dwordx4 v[80:81], v[64:67], off offset:128 nt
	global_store_dwordx4 v[80:81], v[68:71], off offset:144 nt
	global_load_dwordx4 v[66:69], v[86:87], off
	s_nop 0
	global_load_dwordx4 v[70:73], v[86:87], off offset:16
	global_load_dwordx4 v[74:77], v[86:87], off offset:48
	global_load_dwordx4 v[78:81], v[86:87], off offset:32
	v_lshlrev_b64 v[64:65], 10, v[82:83]
	v_lshl_add_u64 v[64:65], v[64:65], 0, v[140:141]
	v_lshlrev_b64 v[86:87], 1, v[64:65]
	v_lshl_add_u64 v[90:91], s[16:17], 0, v[86:87]
	v_lshl_add_u64 v[92:93], s[14:15], 0, v[86:87]
	v_add_u32_e32 v201, 0x48000, v200
	global_load_dwordx4 v[184:187], v201, s[16:17]
	global_load_dwordx4 v[188:191], v201, s[14:15]
	v_lshl_add_u64 v[64:65], v[64:65], 2, s[30:31]
	s_waitcnt vmcnt(5)
	v_mov_b32_e32 v94, v67
	v_mov_b32_e32 v95, v68
	v_mov_b32_e32 v67, v69
	s_waitcnt vmcnt(4)
	v_mov_b32_e32 v68, v71
	v_mov_b32_e32 v69, v72
	v_mov_b32_e32 v71, v73
	v_pk_add_f32 v[66:67], v[94:95], v[66:67]
	v_pk_add_f32 v[68:69], v[68:69], v[70:71]
	v_pk_add_f32 v[66:67], v[66:67], v[66:67] op_sel:[0,1] op_sel_hi:[1,0]
	v_pk_add_f32 v[68:69], v[68:69], v[68:69] op_sel:[0,1] op_sel_hi:[1,0]
	s_waitcnt vmcnt(2)
	v_add_f32_e32 v72, v78, v79
	v_add_f32_e32 v78, v80, v81
	v_mov_b32_e32 v73, v76
	v_mov_b32_e32 v79, v77
	v_mov_b32_e32 v67, v74
	v_mov_b32_e32 v69, v75
	v_pk_add_f32 v[70:71], v[72:73], v[78:79]
	v_pk_add_f32 v[66:67], v[66:67], v[68:69]
	s_waitcnt vmcnt(2)
	v_lshlrev_b32_e32 v76, 16, v192
	v_pk_add_f32 v[66:67], v[66:67], v[70:71]
	v_and_b32_e32 v77, 0xffff0000, v192
	v_add_f32_e32 v66, v66, v67
	v_fmamk_f32 v66, v66, 0x3a800000, v150
	v_mul_f32_e32 v67, 0x4b800000, v66
	v_cmp_gt_f32_e32 vcc, s48, v66
	s_waitcnt vmcnt(2)
	v_lshlrev_b32_e32 v80, 16, v196
	v_and_b32_e32 v81, 0xffff0000, v196
	v_cndmask_b32_e32 v66, v66, v67, vcc
	v_rsq_f32_e32 v68, v66
	v_lshlrev_b32_e32 v82, 16, v193
	v_and_b32_e32 v83, 0xffff0000, v193
	v_lshlrev_b32_e32 v86, 16, v197
	v_mul_f32_e32 v69, 0x45800000, v68
	v_cndmask_b32_e32 v68, v68, v69, vcc
	v_pk_mul_f32 v[62:63], v[62:63], v[68:69] op_sel_hi:[1,0]
	v_pk_mul_f32 v[60:61], v[60:61], v[68:69] op_sel_hi:[1,0]
	v_pk_mul_f32 v[58:59], v[58:59], v[68:69] op_sel_hi:[1,0]
	v_pk_mul_f32 v[56:57], v[56:57], v[68:69] op_sel_hi:[1,0]
	v_mul_f32_e32 v60, 0xbfb8aa3b, v60
	v_mul_f32_e32 v61, 0xbfb8aa3b, v61
	v_mul_f32_e32 v62, 0xbfb8aa3b, v62
	v_mul_f32_e32 v63, 0xbfb8aa3b, v63
	v_mul_f32_e32 v56, 0xbfb8aa3b, v56
	v_mul_f32_e32 v57, 0xbfb8aa3b, v57
	v_mul_f32_e32 v58, 0xbfb8aa3b, v58
	v_mul_f32_e32 v59, 0xbfb8aa3b, v59
	v_exp_f32_e32 v60, v60
	v_exp_f32_e32 v61, v61
	v_exp_f32_e32 v62, v62
	v_exp_f32_e32 v63, v63
	v_exp_f32_e32 v56, v56
	v_exp_f32_e32 v57, v57
	v_exp_f32_e32 v58, v58
	v_exp_f32_e32 v59, v59
	v_add_f32_e32 v60, 1.0, v60
	v_add_f32_e32 v61, 1.0, v61
	v_add_f32_e32 v62, 1.0, v62
	v_add_f32_e32 v63, 1.0, v63
	v_add_f32_e32 v69, 1.0, v56
	v_add_f32_e32 v70, 1.0, v57
	v_add_f32_e32 v71, 1.0, v58
	v_add_f32_e32 v72, 1.0, v59
	v_rcp_f32_e32 v56, v60
	v_rcp_f32_e32 v57, v61
	v_rcp_f32_e32 v58, v62
	v_rcp_f32_e32 v59, v63
	v_rcp_f32_e32 v60, v69
	v_rcp_f32_e32 v61, v70
	v_rcp_f32_e32 v62, v71
	v_rcp_f32_e32 v63, v72
	v_and_b32_e32 v87, 0xffff0000, v197
	v_lshlrev_b32_e32 v96, 16, v194
	v_and_b32_e32 v97, 0xffff0000, v194
	v_lshlrev_b32_e32 v98, 16, v198
	v_and_b32_e32 v99, 0xffff0000, v198
	v_lshlrev_b32_e32 v84, 16, v195
	v_and_b32_e32 v85, 0xffff0000, v195
	v_lshlrev_b32_e32 v66, 16, v199
	v_and_b32_e32 v67, 0xffff0000, v199
	v_pk_fma_f32 v[56:57], v[56:57], v[80:81], v[76:77]
	v_pk_fma_f32 v[58:59], v[58:59], v[86:87], v[82:83]
	v_pk_fma_f32 v[60:61], v[60:61], v[98:99], v[96:97]
	v_pk_fma_f32 v[62:63], v[62:63], v[66:67], v[84:85]
	global_store_dwordx4 v[64:65], v[56:59], off nt
	global_store_dwordx4 v[64:65], v[60:63], off offset:16 nt
	global_load_dwordx4 v[56:59], v[90:91], off offset:64
	s_nop 0
	global_load_dwordx4 v[60:63], v[92:93], off offset:64
	v_pk_mul_f32 v[54:55], v[54:55], v[68:69] op_sel_hi:[1,0]
	v_pk_mul_f32 v[52:53], v[52:53], v[68:69] op_sel_hi:[1,0]
	v_pk_mul_f32 v[50:51], v[50:51], v[68:69] op_sel_hi:[1,0]
	v_pk_mul_f32 v[48:49], v[48:49], v[68:69] op_sel_hi:[1,0]
	v_mul_f32_e32 v52, 0xbfb8aa3b, v52
	v_mul_f32_e32 v53, 0xbfb8aa3b, v53
	v_mul_f32_e32 v54, 0xbfb8aa3b, v54
	v_mul_f32_e32 v55, 0xbfb8aa3b, v55
	v_mul_f32_e32 v48, 0xbfb8aa3b, v48
	v_mul_f32_e32 v49, 0xbfb8aa3b, v49
	v_mul_f32_e32 v50, 0xbfb8aa3b, v50
	v_mul_f32_e32 v51, 0xbfb8aa3b, v51
	v_exp_f32_e32 v52, v52
	v_exp_f32_e32 v53, v53
	v_exp_f32_e32 v54, v54
	v_exp_f32_e32 v55, v55
	v_exp_f32_e32 v48, v48
	v_exp_f32_e32 v49, v49
	v_exp_f32_e32 v50, v50
	v_exp_f32_e32 v51, v51
	v_add_f32_e32 v52, 1.0, v52
	v_add_f32_e32 v53, 1.0, v53
	v_add_f32_e32 v54, 1.0, v54
	v_add_f32_e32 v55, 1.0, v55
	v_add_f32_e32 v68, 1.0, v48
	v_add_f32_e32 v69, 1.0, v49
	v_add_f32_e32 v72, 1.0, v50
	v_add_f32_e32 v73, 1.0, v51
	v_rcp_f32_e32 v48, v52
	v_rcp_f32_e32 v49, v53
	v_rcp_f32_e32 v50, v54
	v_rcp_f32_e32 v51, v55
	v_rcp_f32_e32 v52, v68
	v_rcp_f32_e32 v53, v69
	v_rcp_f32_e32 v54, v72
	v_rcp_f32_e32 v55, v73
	v_add_u32_e32 v66, 0x90, v142
	v_ashrrev_i32_e32 v67, 31, v66
	v_lshlrev_b64 v[70:71], 6, v[66:67]
	v_lshl_add_u64 v[70:71], s[6:7], 0, v[70:71]
	s_waitcnt vmcnt(1)
	v_lshlrev_b32_e32 v68, 16, v56
	v_and_b32_e32 v69, 0xffff0000, v56
	s_waitcnt vmcnt(0)
	v_lshlrev_b32_e32 v72, 16, v60
	v_and_b32_e32 v73, 0xffff0000, v60
	v_lshlrev_b32_e32 v56, 16, v57
	v_and_b32_e32 v57, 0xffff0000, v57
	v_lshlrev_b32_e32 v60, 16, v61
	v_and_b32_e32 v61, 0xffff0000, v61
	v_lshlrev_b32_e32 v74, 16, v58
	v_and_b32_e32 v75, 0xffff0000, v58
	v_lshlrev_b32_e32 v76, 16, v62
	v_and_b32_e32 v77, 0xffff0000, v62
	v_lshlrev_b32_e32 v58, 16, v59
	v_and_b32_e32 v59, 0xffff0000, v59
	v_lshlrev_b32_e32 v62, 16, v63
	v_and_b32_e32 v63, 0xffff0000, v63
	v_pk_fma_f32 v[48:49], v[48:49], v[72:73], v[68:69]
	v_pk_fma_f32 v[50:51], v[50:51], v[60:61], v[56:57]
	v_pk_fma_f32 v[52:53], v[52:53], v[76:77], v[74:75]
	v_pk_fma_f32 v[54:55], v[54:55], v[62:63], v[58:59]
	global_store_dwordx4 v[64:65], v[48:51], off offset:128 nt
	global_store_dwordx4 v[64:65], v[52:55], off offset:144 nt
	global_load_dwordx4 v[50:53], v[70:71], off
	s_nop 0
	global_load_dwordx4 v[54:57], v[70:71], off offset:16
	global_load_dwordx4 v[58:61], v[70:71], off offset:48
	global_load_dwordx4 v[62:65], v[70:71], off offset:32
	v_lshlrev_b64 v[48:49], 10, v[66:67]
	v_lshl_add_u64 v[48:49], v[48:49], 0, v[140:141]
	v_lshlrev_b64 v[70:71], 1, v[48:49]
	v_lshl_add_u64 v[74:75], s[16:17], 0, v[70:71]
	v_lshl_add_u64 v[76:77], s[14:15], 0, v[70:71]
	v_add_u32_e32 v201, 0x50000, v200
	global_load_dwordx4 v[192:195], v201, s[16:17]
	global_load_dwordx4 v[196:199], v201, s[14:15]
	v_lshl_add_u64 v[48:49], v[48:49], 2, s[30:31]
	s_waitcnt vmcnt(5)
	v_mov_b32_e32 v78, v51
	v_mov_b32_e32 v79, v52
	v_mov_b32_e32 v51, v53
	s_waitcnt vmcnt(4)
	v_mov_b32_e32 v52, v55
	v_mov_b32_e32 v53, v56
	v_mov_b32_e32 v55, v57
	v_pk_add_f32 v[50:51], v[78:79], v[50:51]
	v_pk_add_f32 v[52:53], v[52:53], v[54:55]
	v_pk_add_f32 v[50:51], v[50:51], v[50:51] op_sel:[0,1] op_sel_hi:[1,0]
	v_pk_add_f32 v[52:53], v[52:53], v[52:53] op_sel:[0,1] op_sel_hi:[1,0]
	s_waitcnt vmcnt(2)
	v_add_f32_e32 v56, v62, v63
	v_add_f32_e32 v62, v64, v65
	v_mov_b32_e32 v57, v60
	v_mov_b32_e32 v63, v61
	v_mov_b32_e32 v51, v58
	v_mov_b32_e32 v53, v59
	v_pk_add_f32 v[54:55], v[56:57], v[62:63]
	v_pk_add_f32 v[50:51], v[50:51], v[52:53]
	s_waitcnt vmcnt(2)
	v_lshlrev_b32_e32 v60, 16, v184
	v_pk_add_f32 v[50:51], v[50:51], v[54:55]
	v_and_b32_e32 v61, 0xffff0000, v184
	v_add_f32_e32 v50, v50, v51
	v_fmamk_f32 v50, v50, 0x3a800000, v150
	v_mul_f32_e32 v51, 0x4b800000, v50
	v_cmp_gt_f32_e32 vcc, s48, v50
	s_waitcnt vmcnt(2)
	v_lshlrev_b32_e32 v64, 16, v188
	v_and_b32_e32 v65, 0xffff0000, v188
	v_cndmask_b32_e32 v50, v50, v51, vcc
	v_rsq_f32_e32 v52, v50
	v_lshlrev_b32_e32 v66, 16, v185
	v_and_b32_e32 v67, 0xffff0000, v185
	v_lshlrev_b32_e32 v70, 16, v189
	v_mul_f32_e32 v53, 0x45800000, v52
	v_cndmask_b32_e32 v52, v52, v53, vcc
	v_pk_mul_f32 v[46:47], v[46:47], v[52:53] op_sel_hi:[1,0]
	v_pk_mul_f32 v[44:45], v[44:45], v[52:53] op_sel_hi:[1,0]
	v_pk_mul_f32 v[42:43], v[42:43], v[52:53] op_sel_hi:[1,0]
	v_pk_mul_f32 v[40:41], v[40:41], v[52:53] op_sel_hi:[1,0]
	v_mul_f32_e32 v44, 0xbfb8aa3b, v44
	v_mul_f32_e32 v45, 0xbfb8aa3b, v45
	v_mul_f32_e32 v46, 0xbfb8aa3b, v46
	v_mul_f32_e32 v47, 0xbfb8aa3b, v47
	v_mul_f32_e32 v40, 0xbfb8aa3b, v40
	v_mul_f32_e32 v41, 0xbfb8aa3b, v41
	v_mul_f32_e32 v42, 0xbfb8aa3b, v42
	v_mul_f32_e32 v43, 0xbfb8aa3b, v43
	v_exp_f32_e32 v44, v44
	v_exp_f32_e32 v45, v45
	v_exp_f32_e32 v46, v46
	v_exp_f32_e32 v47, v47
	v_exp_f32_e32 v40, v40
	v_exp_f32_e32 v41, v41
	v_exp_f32_e32 v42, v42
	v_exp_f32_e32 v43, v43
	v_add_f32_e32 v44, 1.0, v44
	v_add_f32_e32 v45, 1.0, v45
	v_add_f32_e32 v46, 1.0, v46
	v_add_f32_e32 v47, 1.0, v47
	v_add_f32_e32 v53, 1.0, v40
	v_add_f32_e32 v54, 1.0, v41
	v_add_f32_e32 v55, 1.0, v42
	v_add_f32_e32 v56, 1.0, v43
	v_rcp_f32_e32 v40, v44
	v_rcp_f32_e32 v41, v45
	v_rcp_f32_e32 v42, v46
	v_rcp_f32_e32 v43, v47
	v_rcp_f32_e32 v44, v53
	v_rcp_f32_e32 v45, v54
	v_rcp_f32_e32 v46, v55
	v_rcp_f32_e32 v47, v56
	v_and_b32_e32 v71, 0xffff0000, v189
	v_lshlrev_b32_e32 v80, 16, v186
	v_and_b32_e32 v81, 0xffff0000, v186
	v_lshlrev_b32_e32 v82, 16, v190
	v_and_b32_e32 v83, 0xffff0000, v190
	v_lshlrev_b32_e32 v68, 16, v187
	v_and_b32_e32 v69, 0xffff0000, v187
	v_lshlrev_b32_e32 v50, 16, v191
	v_and_b32_e32 v51, 0xffff0000, v191
	v_pk_fma_f32 v[40:41], v[40:41], v[64:65], v[60:61]
	v_pk_fma_f32 v[42:43], v[42:43], v[70:71], v[66:67]
	v_pk_fma_f32 v[44:45], v[44:45], v[82:83], v[80:81]
	v_pk_fma_f32 v[46:47], v[46:47], v[50:51], v[68:69]
	global_store_dwordx4 v[48:49], v[40:43], off nt
	global_store_dwordx4 v[48:49], v[44:47], off offset:16 nt
	global_load_dwordx4 v[40:43], v[74:75], off offset:64
	s_nop 0
	global_load_dwordx4 v[44:47], v[76:77], off offset:64
	v_pk_mul_f32 v[38:39], v[38:39], v[52:53] op_sel_hi:[1,0]
	v_pk_mul_f32 v[36:37], v[36:37], v[52:53] op_sel_hi:[1,0]
	v_pk_mul_f32 v[34:35], v[34:35], v[52:53] op_sel_hi:[1,0]
	v_pk_mul_f32 v[32:33], v[32:33], v[52:53] op_sel_hi:[1,0]
	v_mul_f32_e32 v36, 0xbfb8aa3b, v36
	v_mul_f32_e32 v37, 0xbfb8aa3b, v37
	v_mul_f32_e32 v38, 0xbfb8aa3b, v38
	v_mul_f32_e32 v39, 0xbfb8aa3b, v39
	v_mul_f32_e32 v32, 0xbfb8aa3b, v32
	v_mul_f32_e32 v33, 0xbfb8aa3b, v33
	v_mul_f32_e32 v34, 0xbfb8aa3b, v34
	v_mul_f32_e32 v35, 0xbfb8aa3b, v35
	v_exp_f32_e32 v36, v36
	v_exp_f32_e32 v37, v37
	v_exp_f32_e32 v38, v38
	v_exp_f32_e32 v39, v39
	v_exp_f32_e32 v32, v32
	v_exp_f32_e32 v33, v33
	v_exp_f32_e32 v34, v34
	v_exp_f32_e32 v35, v35
	v_add_f32_e32 v36, 1.0, v36
	v_add_f32_e32 v37, 1.0, v37
	v_add_f32_e32 v38, 1.0, v38
	v_add_f32_e32 v39, 1.0, v39
	v_add_f32_e32 v52, 1.0, v32
	v_add_f32_e32 v53, 1.0, v33
	v_add_f32_e32 v56, 1.0, v34
	v_add_f32_e32 v57, 1.0, v35
	v_rcp_f32_e32 v32, v36
	v_rcp_f32_e32 v33, v37
	v_rcp_f32_e32 v34, v38
	v_rcp_f32_e32 v35, v39
	v_rcp_f32_e32 v36, v52
	v_rcp_f32_e32 v37, v53
	v_rcp_f32_e32 v38, v56
	v_rcp_f32_e32 v39, v57
	v_add_u32_e32 v50, 0xa0, v142
	v_ashrrev_i32_e32 v51, 31, v50
	v_lshlrev_b64 v[54:55], 6, v[50:51]
	v_lshl_add_u64 v[54:55], s[6:7], 0, v[54:55]
	s_waitcnt vmcnt(1)
	v_lshlrev_b32_e32 v52, 16, v40
	v_and_b32_e32 v53, 0xffff0000, v40
	s_waitcnt vmcnt(0)
	v_lshlrev_b32_e32 v56, 16, v44
	v_and_b32_e32 v57, 0xffff0000, v44
	v_lshlrev_b32_e32 v40, 16, v41
	v_and_b32_e32 v41, 0xffff0000, v41
	v_lshlrev_b32_e32 v44, 16, v45
	v_and_b32_e32 v45, 0xffff0000, v45
	v_lshlrev_b32_e32 v58, 16, v42
	v_and_b32_e32 v59, 0xffff0000, v42
	v_lshlrev_b32_e32 v60, 16, v46
	v_and_b32_e32 v61, 0xffff0000, v46
	v_lshlrev_b32_e32 v42, 16, v43
	v_and_b32_e32 v43, 0xffff0000, v43
	v_lshlrev_b32_e32 v46, 16, v47
	v_and_b32_e32 v47, 0xffff0000, v47
	v_pk_fma_f32 v[32:33], v[32:33], v[56:57], v[52:53]
	v_pk_fma_f32 v[34:35], v[34:35], v[44:45], v[40:41]
	v_pk_fma_f32 v[36:37], v[36:37], v[60:61], v[58:59]
	v_pk_fma_f32 v[38:39], v[38:39], v[46:47], v[42:43]
	global_store_dwordx4 v[48:49], v[32:35], off offset:128 nt
	global_store_dwordx4 v[48:49], v[36:39], off offset:144 nt
	global_load_dwordx4 v[34:37], v[54:55], off
	s_nop 0
	global_load_dwordx4 v[38:41], v[54:55], off offset:16
	global_load_dwordx4 v[42:45], v[54:55], off offset:48
	global_load_dwordx4 v[46:49], v[54:55], off offset:32
	v_lshlrev_b64 v[32:33], 10, v[50:51]
	v_lshl_add_u64 v[32:33], v[32:33], 0, v[140:141]
	v_lshlrev_b64 v[54:55], 1, v[32:33]
	v_lshl_add_u64 v[58:59], s[16:17], 0, v[54:55]
	v_lshl_add_u64 v[60:61], s[14:15], 0, v[54:55]
	v_add_u32_e32 v201, 0x58000, v200
	global_load_dwordx4 v[184:187], v201, s[16:17]
	global_load_dwordx4 v[188:191], v201, s[14:15]
	v_lshl_add_u64 v[32:33], v[32:33], 2, s[30:31]
	s_waitcnt vmcnt(5)
	v_mov_b32_e32 v62, v35
	v_mov_b32_e32 v63, v36
	v_mov_b32_e32 v35, v37
	s_waitcnt vmcnt(4)
	v_mov_b32_e32 v36, v39
	v_mov_b32_e32 v37, v40
	v_mov_b32_e32 v39, v41
	v_pk_add_f32 v[34:35], v[62:63], v[34:35]
	v_pk_add_f32 v[36:37], v[36:37], v[38:39]
	v_pk_add_f32 v[34:35], v[34:35], v[34:35] op_sel:[0,1] op_sel_hi:[1,0]
	v_pk_add_f32 v[36:37], v[36:37], v[36:37] op_sel:[0,1] op_sel_hi:[1,0]
	s_waitcnt vmcnt(2)
	v_add_f32_e32 v40, v46, v47
	v_add_f32_e32 v46, v48, v49
	v_mov_b32_e32 v41, v44
	v_mov_b32_e32 v47, v45
	v_mov_b32_e32 v35, v42
	v_mov_b32_e32 v37, v43
	v_pk_add_f32 v[38:39], v[40:41], v[46:47]
	v_pk_add_f32 v[34:35], v[34:35], v[36:37]
	s_waitcnt vmcnt(2)
	v_lshlrev_b32_e32 v44, 16, v192
	v_pk_add_f32 v[34:35], v[34:35], v[38:39]
	v_and_b32_e32 v45, 0xffff0000, v192
	v_add_f32_e32 v34, v34, v35
	v_fmamk_f32 v34, v34, 0x3a800000, v150
	v_mul_f32_e32 v35, 0x4b800000, v34
	v_cmp_gt_f32_e32 vcc, s48, v34
	s_waitcnt vmcnt(2)
	v_lshlrev_b32_e32 v48, 16, v196
	v_and_b32_e32 v49, 0xffff0000, v196
	v_cndmask_b32_e32 v34, v34, v35, vcc
	v_rsq_f32_e32 v36, v34
	v_lshlrev_b32_e32 v50, 16, v193
	v_and_b32_e32 v51, 0xffff0000, v193
	v_lshlrev_b32_e32 v54, 16, v197
	v_mul_f32_e32 v37, 0x45800000, v36
	v_cndmask_b32_e32 v36, v36, v37, vcc
	v_pk_mul_f32 v[30:31], v[30:31], v[36:37] op_sel_hi:[1,0]
	v_pk_mul_f32 v[28:29], v[28:29], v[36:37] op_sel_hi:[1,0]
	v_pk_mul_f32 v[26:27], v[26:27], v[36:37] op_sel_hi:[1,0]
	v_pk_mul_f32 v[24:25], v[24:25], v[36:37] op_sel_hi:[1,0]
	v_mul_f32_e32 v28, 0xbfb8aa3b, v28
	v_mul_f32_e32 v29, 0xbfb8aa3b, v29
	v_mul_f32_e32 v30, 0xbfb8aa3b, v30
	v_mul_f32_e32 v31, 0xbfb8aa3b, v31
	v_mul_f32_e32 v24, 0xbfb8aa3b, v24
	v_mul_f32_e32 v25, 0xbfb8aa3b, v25
	v_mul_f32_e32 v26, 0xbfb8aa3b, v26
	v_mul_f32_e32 v27, 0xbfb8aa3b, v27
	v_exp_f32_e32 v28, v28
	v_exp_f32_e32 v29, v29
	v_exp_f32_e32 v30, v30
	v_exp_f32_e32 v31, v31
	v_exp_f32_e32 v24, v24
	v_exp_f32_e32 v25, v25
	v_exp_f32_e32 v26, v26
	v_exp_f32_e32 v27, v27
	v_add_f32_e32 v28, 1.0, v28
	v_add_f32_e32 v29, 1.0, v29
	v_add_f32_e32 v30, 1.0, v30
	v_add_f32_e32 v31, 1.0, v31
	v_add_f32_e32 v37, 1.0, v24
	v_add_f32_e32 v38, 1.0, v25
	v_add_f32_e32 v39, 1.0, v26
	v_add_f32_e32 v40, 1.0, v27
	v_rcp_f32_e32 v24, v28
	v_rcp_f32_e32 v25, v29
	v_rcp_f32_e32 v26, v30
	v_rcp_f32_e32 v27, v31
	v_rcp_f32_e32 v28, v37
	v_rcp_f32_e32 v29, v38
	v_rcp_f32_e32 v30, v39
	v_rcp_f32_e32 v31, v40
	v_and_b32_e32 v55, 0xffff0000, v197
	v_lshlrev_b32_e32 v64, 16, v194
	v_and_b32_e32 v65, 0xffff0000, v194
	v_lshlrev_b32_e32 v66, 16, v198
	v_and_b32_e32 v67, 0xffff0000, v198
	v_lshlrev_b32_e32 v52, 16, v195
	v_and_b32_e32 v53, 0xffff0000, v195
	v_lshlrev_b32_e32 v34, 16, v199
	v_and_b32_e32 v35, 0xffff0000, v199
	v_pk_fma_f32 v[24:25], v[24:25], v[48:49], v[44:45]
	v_pk_fma_f32 v[26:27], v[26:27], v[54:55], v[50:51]
	v_pk_fma_f32 v[28:29], v[28:29], v[66:67], v[64:65]
	v_pk_fma_f32 v[30:31], v[30:31], v[34:35], v[52:53]
	global_store_dwordx4 v[32:33], v[24:27], off nt
	global_store_dwordx4 v[32:33], v[28:31], off offset:16 nt
	global_load_dwordx4 v[24:27], v[58:59], off offset:64
	s_nop 0
	global_load_dwordx4 v[28:31], v[60:61], off offset:64
	v_pk_mul_f32 v[22:23], v[22:23], v[36:37] op_sel_hi:[1,0]
	v_pk_mul_f32 v[20:21], v[20:21], v[36:37] op_sel_hi:[1,0]
	v_pk_mul_f32 v[18:19], v[18:19], v[36:37] op_sel_hi:[1,0]
	v_pk_mul_f32 v[16:17], v[16:17], v[36:37] op_sel_hi:[1,0]
	v_mul_f32_e32 v20, 0xbfb8aa3b, v20
	v_mul_f32_e32 v21, 0xbfb8aa3b, v21
	v_mul_f32_e32 v22, 0xbfb8aa3b, v22
	v_mul_f32_e32 v23, 0xbfb8aa3b, v23
	v_mul_f32_e32 v16, 0xbfb8aa3b, v16
	v_mul_f32_e32 v17, 0xbfb8aa3b, v17
	v_mul_f32_e32 v18, 0xbfb8aa3b, v18
	v_mul_f32_e32 v19, 0xbfb8aa3b, v19
	v_exp_f32_e32 v20, v20
	v_exp_f32_e32 v21, v21
	v_exp_f32_e32 v22, v22
	v_exp_f32_e32 v23, v23
	v_exp_f32_e32 v16, v16
	v_exp_f32_e32 v17, v17
	v_exp_f32_e32 v18, v18
	v_exp_f32_e32 v19, v19
	v_add_f32_e32 v20, 1.0, v20
	v_add_f32_e32 v21, 1.0, v21
	v_add_f32_e32 v22, 1.0, v22
	v_add_f32_e32 v23, 1.0, v23
	v_add_f32_e32 v36, 1.0, v16
	v_add_f32_e32 v37, 1.0, v17
	v_add_f32_e32 v40, 1.0, v18
	v_add_f32_e32 v41, 1.0, v19
	v_rcp_f32_e32 v16, v20
	v_rcp_f32_e32 v17, v21
	v_rcp_f32_e32 v18, v22
	v_rcp_f32_e32 v19, v23
	v_rcp_f32_e32 v20, v36
	v_rcp_f32_e32 v21, v37
	v_rcp_f32_e32 v22, v40
	v_rcp_f32_e32 v23, v41
	v_add_u32_e32 v34, 0xb0, v142
	v_ashrrev_i32_e32 v35, 31, v34
	v_lshlrev_b64 v[38:39], 6, v[34:35]
	v_lshl_add_u64 v[38:39], s[6:7], 0, v[38:39]
	s_waitcnt vmcnt(1)
	v_lshlrev_b32_e32 v36, 16, v24
	v_and_b32_e32 v37, 0xffff0000, v24
	s_waitcnt vmcnt(0)
	v_lshlrev_b32_e32 v40, 16, v28
	v_and_b32_e32 v41, 0xffff0000, v28
	v_lshlrev_b32_e32 v24, 16, v25
	v_and_b32_e32 v25, 0xffff0000, v25
	v_lshlrev_b32_e32 v28, 16, v29
	v_and_b32_e32 v29, 0xffff0000, v29
	v_lshlrev_b32_e32 v42, 16, v26
	v_and_b32_e32 v43, 0xffff0000, v26
	v_lshlrev_b32_e32 v44, 16, v30
	v_and_b32_e32 v45, 0xffff0000, v30
	v_lshlrev_b32_e32 v26, 16, v27
	v_and_b32_e32 v27, 0xffff0000, v27
	v_lshlrev_b32_e32 v30, 16, v31
	v_and_b32_e32 v31, 0xffff0000, v31
	v_pk_fma_f32 v[16:17], v[16:17], v[40:41], v[36:37]
	v_pk_fma_f32 v[18:19], v[18:19], v[28:29], v[24:25]
	v_pk_fma_f32 v[20:21], v[20:21], v[44:45], v[42:43]
	v_pk_fma_f32 v[22:23], v[22:23], v[30:31], v[26:27]
	global_store_dwordx4 v[32:33], v[16:19], off offset:128 nt
	global_store_dwordx4 v[32:33], v[20:23], off offset:144 nt
	global_load_dwordx4 v[16:19], v[38:39], off
	s_nop 0
	global_load_dwordx4 v[20:23], v[38:39], off offset:16
	global_load_dwordx4 v[24:27], v[38:39], off offset:48
	global_load_dwordx4 v[28:31], v[38:39], off offset:32
	v_lshlrev_b64 v[32:33], 10, v[34:35]
	v_lshl_add_u64 v[40:41], v[32:33], 0, v[140:141]
	v_lshlrev_b64 v[36:37], 1, v[40:41]
	v_lshl_add_u64 v[42:43], s[16:17], 0, v[36:37]
	v_lshl_add_u64 v[44:45], s[14:15], 0, v[36:37]
	v_lshl_add_u64 v[40:41], v[40:41], 2, s[30:31]
	s_waitcnt vmcnt(3)
	v_mov_b32_e32 v46, v17
	v_mov_b32_e32 v47, v18
	v_mov_b32_e32 v17, v19
	s_waitcnt vmcnt(2)
	v_mov_b32_e32 v18, v21
	v_mov_b32_e32 v19, v22
	v_mov_b32_e32 v21, v23
	v_pk_add_f32 v[16:17], v[46:47], v[16:17]
	v_pk_add_f32 v[18:19], v[18:19], v[20:21]
	v_pk_add_f32 v[16:17], v[16:17], v[16:17] op_sel:[0,1] op_sel_hi:[1,0]
	v_pk_add_f32 v[18:19], v[18:19], v[18:19] op_sel:[0,1] op_sel_hi:[1,0]
	s_waitcnt vmcnt(0)
	v_add_f32_e32 v22, v28, v29
	v_add_f32_e32 v28, v30, v31
	v_mov_b32_e32 v23, v26
	v_mov_b32_e32 v29, v27
	v_mov_b32_e32 v17, v24
	v_mov_b32_e32 v19, v25
	v_pk_add_f32 v[20:21], v[22:23], v[28:29]
	v_pk_add_f32 v[16:17], v[16:17], v[18:19]
	s_waitcnt vmcnt(0)
	v_lshlrev_b32_e32 v26, 16, v184
	v_pk_add_f32 v[16:17], v[16:17], v[20:21]
	v_and_b32_e32 v27, 0xffff0000, v184
	v_add_f32_e32 v16, v16, v17
	v_fmamk_f32 v16, v16, 0x3a800000, v150
	v_mul_f32_e32 v17, 0x4b800000, v16
	v_cmp_gt_f32_e32 vcc, s48, v16
	s_waitcnt vmcnt(0)
	v_lshlrev_b32_e32 v30, 16, v188
	v_and_b32_e32 v31, 0xffff0000, v188
	v_cndmask_b32_e32 v16, v16, v17, vcc
	v_rsq_f32_e32 v18, v16
	v_lshlrev_b32_e32 v32, 16, v185
	v_and_b32_e32 v33, 0xffff0000, v185
	v_lshlrev_b32_e32 v36, 16, v189
	v_mul_f32_e32 v19, 0x45800000, v18
	v_cndmask_b32_e32 v18, v18, v19, vcc
	v_pk_mul_f32 v[14:15], v[14:15], v[18:19] op_sel_hi:[1,0]
	v_pk_mul_f32 v[12:13], v[12:13], v[18:19] op_sel_hi:[1,0]
	v_pk_mul_f32 v[10:11], v[10:11], v[18:19] op_sel_hi:[1,0]
	v_pk_mul_f32 v[8:9], v[8:9], v[18:19] op_sel_hi:[1,0]
	v_mul_f32_e32 v12, 0xbfb8aa3b, v12
	v_mul_f32_e32 v13, 0xbfb8aa3b, v13
	v_mul_f32_e32 v14, 0xbfb8aa3b, v14
	v_mul_f32_e32 v15, 0xbfb8aa3b, v15
	v_mul_f32_e32 v8, 0xbfb8aa3b, v8
	v_mul_f32_e32 v9, 0xbfb8aa3b, v9
	v_mul_f32_e32 v10, 0xbfb8aa3b, v10
	v_mul_f32_e32 v11, 0xbfb8aa3b, v11
	v_exp_f32_e32 v12, v12
	v_exp_f32_e32 v13, v13
	v_exp_f32_e32 v14, v14
	v_exp_f32_e32 v15, v15
	v_exp_f32_e32 v8, v8
	v_exp_f32_e32 v9, v9
	v_exp_f32_e32 v10, v10
	v_exp_f32_e32 v11, v11
	v_add_f32_e32 v12, 1.0, v12
	v_add_f32_e32 v13, 1.0, v13
	v_add_f32_e32 v14, 1.0, v14
	v_add_f32_e32 v15, 1.0, v15
	v_add_f32_e32 v19, 1.0, v8
	v_add_f32_e32 v20, 1.0, v9
	v_add_f32_e32 v21, 1.0, v10
	v_add_f32_e32 v22, 1.0, v11
	v_rcp_f32_e32 v8, v12
	v_rcp_f32_e32 v9, v13
	v_rcp_f32_e32 v10, v14
	v_rcp_f32_e32 v11, v15
	v_rcp_f32_e32 v12, v19
	v_rcp_f32_e32 v13, v20
	v_rcp_f32_e32 v14, v21
	v_rcp_f32_e32 v15, v22
	v_and_b32_e32 v37, 0xffff0000, v189
	v_lshlrev_b32_e32 v48, 16, v186
	v_and_b32_e32 v49, 0xffff0000, v186
	v_lshlrev_b32_e32 v50, 16, v190
	v_and_b32_e32 v51, 0xffff0000, v190
	v_lshlrev_b32_e32 v34, 16, v187
	v_and_b32_e32 v35, 0xffff0000, v187
	v_lshlrev_b32_e32 v16, 16, v191
	v_and_b32_e32 v17, 0xffff0000, v191
	v_pk_fma_f32 v[8:9], v[8:9], v[30:31], v[26:27]
	v_pk_fma_f32 v[10:11], v[10:11], v[36:37], v[32:33]
	v_pk_fma_f32 v[12:13], v[12:13], v[50:51], v[48:49]
	v_pk_fma_f32 v[14:15], v[14:15], v[16:17], v[34:35]
	global_store_dwordx4 v[40:41], v[8:11], off nt
	global_store_dwordx4 v[40:41], v[12:15], off offset:16 nt
	global_load_dwordx4 v[8:11], v[42:43], off offset:64
	s_nop 0
	global_load_dwordx4 v[12:15], v[44:45], off offset:64
	v_pk_mul_f32 v[6:7], v[6:7], v[18:19] op_sel_hi:[1,0]
	v_pk_mul_f32 v[4:5], v[4:5], v[18:19] op_sel_hi:[1,0]
	v_pk_mul_f32 v[2:3], v[2:3], v[18:19] op_sel_hi:[1,0]
	v_pk_mul_f32 v[0:1], v[0:1], v[18:19] op_sel_hi:[1,0]
	v_mul_f32_e32 v4, 0xbfb8aa3b, v4
	v_mul_f32_e32 v5, 0xbfb8aa3b, v5
	v_mul_f32_e32 v6, 0xbfb8aa3b, v6
	v_mul_f32_e32 v7, 0xbfb8aa3b, v7
	v_mul_f32_e32 v0, 0xbfb8aa3b, v0
	v_mul_f32_e32 v1, 0xbfb8aa3b, v1
	v_mul_f32_e32 v2, 0xbfb8aa3b, v2
	v_mul_f32_e32 v3, 0xbfb8aa3b, v3
	v_exp_f32_e32 v4, v4
	v_exp_f32_e32 v5, v5
	v_exp_f32_e32 v6, v6
	v_exp_f32_e32 v7, v7
	v_exp_f32_e32 v0, v0
	v_exp_f32_e32 v1, v1
	v_exp_f32_e32 v2, v2
	v_exp_f32_e32 v3, v3
	v_add_f32_e32 v4, 1.0, v4
	v_add_f32_e32 v5, 1.0, v5
	v_add_f32_e32 v6, 1.0, v6
	v_add_f32_e32 v7, 1.0, v7
	v_add_f32_e32 v16, 1.0, v0
	v_add_f32_e32 v17, 1.0, v1
	v_add_f32_e32 v18, 1.0, v2
	v_add_f32_e32 v19, 1.0, v3
	v_rcp_f32_e32 v0, v4
	v_rcp_f32_e32 v1, v5
	v_rcp_f32_e32 v2, v6
	v_rcp_f32_e32 v3, v7
	v_rcp_f32_e32 v4, v16
	v_rcp_f32_e32 v5, v17
	v_rcp_f32_e32 v6, v18
	v_rcp_f32_e32 v7, v19
	s_andn2_b64 vcc, exec, s[0:1]
	s_mov_b64 s[0:1], -1
	s_waitcnt vmcnt(1)
	v_lshlrev_b32_e32 v16, 16, v8
	v_and_b32_e32 v17, 0xffff0000, v8
	s_waitcnt vmcnt(0)
	v_lshlrev_b32_e32 v18, 16, v12
	v_and_b32_e32 v19, 0xffff0000, v12
	v_lshlrev_b32_e32 v8, 16, v9
	v_and_b32_e32 v9, 0xffff0000, v9
	v_lshlrev_b32_e32 v12, 16, v13
	v_and_b32_e32 v13, 0xffff0000, v13
	v_lshlrev_b32_e32 v20, 16, v10
	v_and_b32_e32 v21, 0xffff0000, v10
	v_lshlrev_b32_e32 v22, 16, v14
	v_and_b32_e32 v23, 0xffff0000, v14
	v_lshlrev_b32_e32 v10, 16, v11
	v_and_b32_e32 v11, 0xffff0000, v11
	v_lshlrev_b32_e32 v14, 16, v15
	v_and_b32_e32 v15, 0xffff0000, v15
	v_pk_fma_f32 v[0:1], v[0:1], v[18:19], v[16:17]
	v_pk_fma_f32 v[2:3], v[2:3], v[12:13], v[8:9]
	v_pk_fma_f32 v[4:5], v[4:5], v[22:23], v[20:21]
	v_pk_fma_f32 v[6:7], v[6:7], v[14:15], v[10:11]
	global_store_dwordx4 v[40:41], v[0:3], off offset:128 nt
	global_store_dwordx4 v[40:41], v[4:7], off offset:144 nt
	s_cbranch_vccnz .LBB0_466
	s_andn2_b64 vcc, exec, s[4:5]
	s_cbranch_vccnz .LBB0_465
	s_barrier
	s_branch .LBB0_465
